# all bit-exact edits stacked: lambda cache, CMP batching, peeled zero-accumulator K-loop entry, no setprio flips, dwordx4 attention store tail, next-ticket atomic issued at the head of the store tail
# speedup vs baseline: 1.0081x; 1.0023x over previous
; DI float ex2(float x) { return __builtin_amdgcn_exp2f(x); }
; DI void attn_unit(const Params& p, int l, int b, int qtp, int grp, char* smem) {
;     ...
;     const float lam_init = 0.8f - 0.6f * __expf(-0.3f * (float)l);
;     float d1 = 0.f, d2 = 0.f;
;     for (int i = 0; i < 32; ++i) { d1 += p.lq1[l * 32 + i] * p.lk1[l * 32 + i]; d2 += p.lq2[l * 32 + i] * p.lk2[l * 32 + i]; }
;     const float lam = __expf(d1) - __expf(d2) + lam_init;
;     const float slope2 = ex2(-(2.f / 3.f) * (float)(3 * w + 2)) * LOG2E;
;     const float scale2 = 0.17677669529663687f * LOG2E;
; DI void phase_attn(const Params& p, int l, char* smem) {
;   int* ctr = (int*)(p.ws + OFF_CTR) + l * 8;
;   int* su = (int*)(smem + 35072);
;   const int xcd = blockIdx.x & 7;
;   int k = 0;
.LBB0_108:
	s_mov_b32 s99, 0
	s_mov_b32 s101, 0
	v_readlane_b32 s0, v245, 53
	v_readlane_b32 s1, v245, 54
	s_mov_b32 s4, s0
	s_lshl_b32 s0, s0, 3
	s_ashr_i32 s1, s0, 31
	s_lshl_b64 s[0:1], s[0:1], 2
	v_readlane_b32 s2, v246, 2
	v_readlane_b32 s3, v246, 3
	s_add_u32 s0, s2, s0
	s_addc_u32 s1, s3, s1
	v_writelane_b32 v245, s0, 58
	v_cvt_f32_i32_e32 v0, s4
	s_lshl_b32 s2, s4, 2
	v_writelane_b32 v245, s1, 59
	s_lshl_b32 s0, s4, 5
	s_ashr_i32 s1, s0, 31
	v_readlane_b32 s4, v247, 45
	s_lshl_b64 s[0:1], s[0:1], 2
	v_readlane_b32 s8, v247, 49
	v_writelane_b32 v245, s2, 60
	v_readlane_b32 s9, v247, 50
	s_add_u32 s2, s8, s0
	s_addc_u32 s3, s9, s1
	v_readlane_b32 s10, v247, 51
	v_writelane_b32 v245, s2, 61
	v_mul_f32_e32 v0, 0xbe99999a, v0
	v_readlane_b32 s11, v247, 52
	v_writelane_b32 v245, s3, 62
	s_add_u32 s2, s10, s0
	v_mul_f32_e32 v0, 0x3fb8aa3b, v0
	s_addc_u32 s3, s11, s1
	v_exp_f32_e32 v0, v0
	v_readlane_b32 s12, v247, 53
	v_writelane_b32 v245, s2, 63
	v_readlane_b32 s13, v247, 54
	v_readlane_b32 s14, v247, 55
	v_writelane_b32 v244, s3, 0
	s_add_u32 s2, s12, s0
	s_addc_u32 s3, s13, s1
	v_readlane_b32 s15, v247, 56
	v_writelane_b32 v244, s2, 1
	s_add_u32 s0, s14, s0
	v_fmamk_f32 v213, v0, 0xbf19999a, v155
	v_writelane_b32 v244, s3, 2
	s_addc_u32 s1, s15, s1
	v_sub_f32_e32 v214, 1.0, v213
	v_writelane_b32 v244, s0, 3
	v_mov_b32_e32 v215, 0
	v_readlane_b32 s5, v247, 46
	v_readlane_b32 s6, v247, 47
	v_readlane_b32 s7, v247, 48
	v_readlane_b32 s16, v247, 57
	v_readlane_b32 s17, v247, 58
	v_readlane_b32 s18, v247, 59
	v_readlane_b32 s19, v247, 60
	v_writelane_b32 v244, s1, 4
	s_branch .LBB0_111

; DI int my_tid() { int t = threadIdx.x; asm volatile("" : "+v"(t)); return t; }
; DI unsigned pk2(float a, float b) { f32x2 v = {a, b}; bf2_t r = __builtin_convertvector(v, bf2_t); return __builtin_bit_cast(unsigned, r); }
; DI void attn_unit(const Params& p, int l, int b, int qtp, int grp, char* smem) {
;     ...
;   const int gcol = (grp == 2 ? 0 : grp == 1 ? 256 : grp == 0 ? 512 : 768) + w * 64 + 4 * h;
;   bf16_t* mrow = (bf16_t*)(p.ws + OFF_MIX) + (tok0 + qpos) * DM + gcol;
; #pragma unroll
;   for (int g = 0; g < 4; ++g) {
;     u32x2 a = {pk2(o0[4 * g], o0[4 * g + 1]), pk2(o0[4 * g + 2], o0[4 * g + 3])};
;     u32x2 c = {pk2(o1[4 * g], o1[4 * g + 1]), pk2(o1[4 * g + 2], o1[4 * g + 3])};
;     *(u32x2*)(mrow + 8 * g) = a;
;     *(u32x2*)(mrow + 32 + 8 * g) = c;
;   }
;   __syncthreads();
; DI void phase_attn(const Params& p, int l, char* smem) {
;     ...
;     if (my_tid() == 0) {
;       int U = -1;
;       for (; k < 8; ++k) {
;         const int x = (xcd + k) & 7;
;         const int v = atomicAdd(ctr + x, 1);
;         if (v < 512) { U = x * 512 + v; break; }
.LBB0_110:
	v_cmp_eq_u32_e32 vcc, 0, v152
	s_and_b64 exec, exec, vcc
	s_cbranch_execz .Lpf3_skip
	v_cmp_gt_i32_e32 vcc, 8, v215
	s_and_b64 exec, exec, vcc
	s_cbranch_execz .Lpf3_skip
	v_add_u32_e32 v54, s68, v215
	v_and_b32_e32 v54, 7, v54
	v_lshlrev_b32_e32 v54, 2, v54
	v_readlane_b32 vcc_lo, v245, 58
	v_readlane_b32 vcc_hi, v245, 59
	s_nop 4
	global_atomic_add v55, v54, v200, vcc sc0
	s_mov_b32 s99, 1
.Lpf3_skip:
	s_mov_b64 exec, -1
	v_readlane_b32 s1, v244, 21
	s_cmp_lg_u32 s1, 1
	s_cselect_b32 s2, s0, 0x100
	v_readlane_b32 s0, v244, 9
	v_readlane_b32 s1, v244, 10
	s_and_b64 s[0:1], s[0:1], exec
	s_cselect_b32 s0, 0, s2
	v_or3_b32 v0, v159, v220, s0
	v_readlane_b32 s0, v246, 16
	v_lshlrev_b64 v[34:35], 11, v[156:157]
	v_readlane_b32 s1, v246, 17
	s_waitcnt vmcnt(0)
	v_lshl_add_u64 v[34:35], s[0:1], 0, v[34:35]
	v_lshl_add_u64 v[34:35], v[0:1], 1, v[34:35]
	v_cvt_pk_bf16_f32 v36, v18, v19
	v_cvt_pk_bf16_f32 v37, v20, v21
	v_cvt_pk_bf16_f32 v38, v22, v23
	v_cvt_pk_bf16_f32 v39, v24, v25
	v_cvt_pk_bf16_f32 v40, v26, v27
	v_cvt_pk_bf16_f32 v41, v28, v29
	v_cvt_pk_bf16_f32 v42, v30, v31
	v_cvt_pk_bf16_f32 v43, v32, v33
	v_cvt_pk_bf16_f32 v44, v2, v3
	v_cvt_pk_bf16_f32 v45, v4, v5
	v_cvt_pk_bf16_f32 v46, v6, v7
	v_cvt_pk_bf16_f32 v47, v8, v9
	v_cvt_pk_bf16_f32 v48, v10, v11
	v_cvt_pk_bf16_f32 v49, v12, v13
	v_cvt_pk_bf16_f32 v50, v14, v15
	v_cvt_pk_bf16_f32 v51, v16, v17
	v_and_b32_e32 v52, 32, v203
	v_lshrrev_b32_e32 v52, 2, v52
	v_mov_b32_e32 v53, 0
	v_lshl_add_u64 v[34:35], v[34:35], 0, v[52:53]
	v_permlane32_swap_b32_e32 v36, v38
	v_permlane32_swap_b32_e32 v37, v39
	v_permlane32_swap_b32_e32 v40, v42
	v_permlane32_swap_b32_e32 v41, v43
	v_permlane32_swap_b32_e32 v44, v46
	v_permlane32_swap_b32_e32 v45, v47
	v_permlane32_swap_b32_e32 v48, v50
	v_permlane32_swap_b32_e32 v49, v51
	global_store_dwordx4 v[34:35], v[36:39], off
	global_store_dwordx4 v[34:35], v[40:43], off offset:32
	global_store_dwordx4 v[34:35], v[44:47], off offset:64
	global_store_dwordx4 v[34:35], v[48:51], off offset:96
	s_barrier

; DI int my_tid() { int t = threadIdx.x; asm volatile("" : "+v"(t)); return t; }
; DI void phase_attn(const Params& p, int l, char* smem) {
;     ...
;     if (my_tid() == 0) {
;       int U = -1;
;       for (; k < 8; ++k) {
;         const int x = (xcd + k) & 7;
;         const int v = atomicAdd(ctr + x, 1);
;         if (v < 512) { U = x * 512 + v; break; }
;       }
;       *su = U;
;     }
;     __syncthreads();
;     const int U = *su;
;     __syncthreads();
;     if (U < 0) break;
.LBB0_115:
	v_mov_b32_e32 v0, v215
	s_waitcnt lgkmcnt(0)
	v_add_u32_e32 v2, s68, v0
	v_and_b32_e32 v2, 7, v2
	v_readlane_b32 s12, v245, 58
	v_lshlrev_b32_e32 v3, 2, v2
	v_readlane_b32 s13, v245, 59
	s_or_b64 s[8:9], s[8:9], exec
	s_or_b64 s[10:11], s[10:11], exec
	s_nop 2
	s_cmp_eq_u32 s99, 0
	s_cbranch_scc0 .Lpf_use
	global_atomic_add v3, v3, v200, s[12:13] sc0
	s_branch .Lpf_join
.Lpf_use:
	s_waitcnt vmcnt(0)
	v_mov_b32_e32 v3, v55
	s_mov_b32 s99, 0
.Lpf_join:
	s_movk_i32 s12, 0x1ff
	s_waitcnt vmcnt(0)
	v_cmp_lt_i32_e32 vcc, s12, v3
	s_and_saveexec_b64 s[12:13], vcc
	s_cbranch_execz .LBB0_114
	v_cmp_lt_i32_e32 vcc, 6, v0
	s_andn2_b64 s[10:11], s[10:11], exec
	s_and_b64 s[14:15], vcc, exec
	v_add_u32_e32 v215, 1, v0
	s_andn2_b64 s[8:9], s[8:9], exec
	s_or_b64 s[10:11], s[10:11], s[14:15]
	s_branch .LBB0_114
